# mem attention K/V staging: all four rounds of loads issued up front with counted waits (one exposed latency instead of four)
# baseline (speedup 1.0000x reference)
; __device__ __forceinline__ int v_st(int k, int c) { const int kk = (k & ~0xC) | ((k & 4) << 1) | ((k & 8) >> 1); return ((kk >> 3) * 4 + (c >> 5)) * 512 + ((kk & 7) * 32 + (c & 31)) * 2; }
; __device__ __forceinline__ int v_rd_base(int lane) { return ((lane & 3) << 3) | (((lane >> 2) & 3) << 6) | (((lane >> 4) & 1) << 5) | (((lane >> 5) & 1) << 8); }
; #define ATT_SLOAD(st, key0) do { st.v0 = *(const bf16x8*)(Vh + (size_t)((key0) + sr) * LDK + sc); st.v1 = *(const bf16x8*)(Vh + (size_t)((key0) + 32 + sr) * LDK + sc); \
;     st.k0 = *(const bf16x8*)(Kh + (size_t)((key0) + sr) * LDK + sc); st.k1 = *(const bf16x8*)(Kh + (size_t)((key0) + 32 + sr) * LDK + sc); } while (0)
; #define ATT_SWRITE(vbuf, kbuf, st) do { *(LAS bf16x8*)((vbuf) + vst0) = st.v0; *(LAS bf16x8*)((vbuf) + vst1) = st.v1; \
;     *(LAS bf16x8*)((kbuf) + KSWZ(sr, sc * 2)) = st.k0; *(LAS bf16x8*)((kbuf) + KSWZ(32 + sr, sc * 2)) = st.k1; } while (0)
; template <int LDQ, int LDK, int LDO>
; __device__ __forceinline__ void mem_unit(const bf16* __restrict__ Qb0, const bf16* __restrict__ Kh, const bf16* __restrict__ Vh, bf16* __restrict__ Ob0, int nq, LAS char* lds, LAS float* ws) {
;     ...
;     const int sr = tid >> 4, sc = (tid & 15) * 8, vst0 = v_st(sr, sc), vst1 = v_st(32 + sr, sc);
;     const int vb0 = (int)(uintptr_t)V_lds + v_rd_base(lane);
; #pragma unroll
;     for (int t = 0; t < 4; ++t) { Stg st; ATT_SLOAD(st, t * KVBLK); ATT_SWRITE(V_lds + t * SHM_T, K_lds + t * SHM_T, st); }
;     __syncthreads();
.LBB0_504:
	s_ashr_i32 s2, s8, 5
	s_lshl_b32 s0, s8, 9
	s_ashr_i32 s3, s2, 31
	s_and_b32 s0, s0, 0xe00
	s_lshl_b64 s[4:5], s[2:3], 12
	s_or_b32 s4, s4, s0
	s_lshl_b64 s[0:1], s[4:5], 10
	v_readlane_b32 s6, v250, 27
	v_readlane_b32 s7, v250, 28
	s_add_u32 s0, s6, s0
	s_addc_u32 s1, s7, s1
	s_lshl_b32 s6, s8, 5
	v_mov_b32_e32 v5, v0
	s_and_b32 s6, s6, 0x300
	s_add_u32 s0, s0, s6
	v_ashrrev_i32_e32 v8, 4, v5
	v_and_b32_e32 v7, 0xfffff0, v8
	v_lshlrev_b32_e32 v9, 1, v8
	s_addc_u32 s1, s1, 0
	s_lshl_b64 s[2:3], s[2:3], 21
	v_readlane_b32 s7, v254, 53
	v_lshlrev_b32_e32 v3, 3, v5
	v_and_or_b32 v7, v9, 8, v7
	s_add_u32 s2, s7, s2
	v_readlane_b32 s7, v254, 54
	v_and_b32_e32 v6, 0x78, v3
	v_lshrrev_b32_e32 v7, 1, v7
	v_bfe_u32 v3, v3, 5, 2
	s_addc_u32 s3, s7, s3
	v_or_b32_e32 v7, v7, v3
	s_add_u32 s2, s2, s6
	v_lshrrev_b32_e32 v9, 1, v8
	v_lshlrev_b32_e32 v26, 9, v7
	v_and_b32_e32 v7, 3, v8
	s_addc_u32 s3, s3, 0
	v_and_or_b32 v27, v9, 4, v7
	v_lshlrev_b32_e32 v98, 1, v6
	v_ashrrev_i32_e32 v9, 31, v8
	v_add_u32_e32 v12, 32, v8
	v_lshl_add_u64 v[14:15], s[2:3], 0, v[98:99]
	v_lshlrev_b32_e32 v30, 8, v8
	v_lshlrev_b64 v[8:9], 13, v[8:9]
	v_lshl_add_u64 v[24:25], v[14:15], 0, v[8:9]
	v_ashrrev_i32_e32 v13, 31, v12
	v_and_b32_e32 v6, 0xfffff0, v12
	v_lshlrev_b32_e32 v7, 1, v12
	v_lshlrev_b32_e32 v32, 8, v12
	global_load_dwordx4 v[8:11], v[24:25], off offset:1024
	v_lshlrev_b64 v[12:13], 13, v[12:13]
	v_lshl_add_u64 v[20:21], v[14:15], 0, v[12:13]
	global_load_dwordx4 v[12:15], v[20:21], off offset:1024
	global_load_dwordx4 v[16:19], v[24:25], off
	s_nop 0
	global_load_dwordx4 v[20:23], v[20:21], off
	s_mov_b32 s101, 0
	s_mov_b32 s100, 0x80000
	v_lshl_add_u64 v[52:53], v[24:25], 0, s[100:101]
	s_mov_b32 s100, 0xc0000
	v_lshl_add_u64 v[54:55], v[24:25], 0, s[100:101]
	global_load_dwordx4 v[100:103], v[52:53], off offset:1024
	global_load_dwordx4 v[104:107], v[54:55], off offset:1024
	global_load_dwordx4 v[108:111], v[52:53], off
	global_load_dwordx4 v[112:115], v[54:55], off
	s_mov_b32 s100, 0x100000
	v_lshl_add_u64 v[52:53], v[24:25], 0, s[100:101]
	s_mov_b32 s100, 0x140000
	v_lshl_add_u64 v[54:55], v[24:25], 0, s[100:101]
	global_load_dwordx4 v[116:119], v[52:53], off offset:1024
	global_load_dwordx4 v[120:123], v[54:55], off offset:1024
	global_load_dwordx4 v[124:127], v[52:53], off
	global_load_dwordx4 v[128:131], v[54:55], off
	s_mov_b32 s100, 0x180000
	v_lshl_add_u64 v[52:53], v[24:25], 0, s[100:101]
	s_mov_b32 s100, 0x1c0000
	v_lshl_add_u64 v[54:55], v[24:25], 0, s[100:101]
	global_load_dwordx4 v[36:39], v[52:53], off offset:1024
	global_load_dwordx4 v[40:43], v[54:55], off offset:1024
	global_load_dwordx4 v[44:47], v[52:53], off
	global_load_dwordx4 v[48:51], v[54:55], off
	s_lshl_b64 s[4:5], s[4:5], 12
	s_add_u32 s4, s33, s4
	v_and_or_b32 v6, v7, 8, v6
	s_addc_u32 s5, s54, s5
	v_lshrrev_b32_e32 v6, 1, v6
	s_add_u32 s4, s4, s6
	v_and_b32_e32 v28, 48, v98
	v_or_b32_e32 v3, v6, v3
	s_movk_i32 s2, 0x70
	v_lshl_add_u32 v27, v27, 6, 0
	s_addc_u32 s5, s5, 0
	v_lshlrev_b32_e32 v29, 9, v3
	v_bitop3_b32 v31, v98, v5, s2 bitop3:0x78
	v_add3_u32 v26, v27, v26, v28
	s_add_i32 s2, 0, 0x10000
	v_add3_u32 v27, v27, v29, v28
	v_and_b32_e32 v2, 31, v5
	v_lshlrev_b32_e32 v6, 4, v5
	v_and_b32_e32 v4, 63, v5
	v_lshlrev_b32_e32 v3, 1, v5
	v_readlane_b32 s6, v251, 53
	v_lshlrev_b32_e32 v98, 1, v2
	v_lshlrev_b32_e32 v7, 3, v4
	v_lshl_add_u32 v176, v2, 2, s6
	v_and_b32_e32 v3, 32, v3
	s_waitcnt vmcnt(62)
; #define ATT_SLOAD(st, key0) do { st.v0 = *(const bf16x8*)(Vh + (size_t)((key0) + sr) * LDK + sc); st.v1 = *(const bf16x8*)(Vh + (size_t)((key0) + 32 + sr) * LDK + sc); \
;     st.k0 = *(const bf16x8*)(Kh + (size_t)((key0) + sr) * LDK + sc); st.k1 = *(const bf16x8*)(Kh + (size_t)((key0) + 32 + sr) * LDK + sc); } while (0)
; #define ATT_SWRITE(vbuf, kbuf, st) do { *(LAS bf16x8*)((vbuf) + vst0) = st.v0; *(LAS bf16x8*)((vbuf) + vst1) = st.v1; \
;     *(LAS bf16x8*)((kbuf) + KSWZ(sr, sc * 2)) = st.k0; *(LAS bf16x8*)((kbuf) + KSWZ(32 + sr, sc * 2)) = st.k1; } while (0)
; template <int LDQ, int LDK, int LDO>
; __device__ __forceinline__ void mem_unit(const bf16* __restrict__ Qb0, const bf16* __restrict__ Kh, const bf16* __restrict__ Vh, bf16* __restrict__ Ob0, int nq, LAS char* lds, LAS float* ws) {
;     ...
;     for (int t = 0; t < 4; ++t) { Stg st; ATT_SLOAD(st, t * KVBLK); ATT_SWRITE(V_lds + t * SHM_T, K_lds + t * SHM_T, st); }
;     __syncthreads();
	v_mov_b32_e32 v137, v99
	v_mov_b32_e32 v139, v99
	v_mov_b32_e32 v141, v99
	v_mov_b32_e32 v143, v99
	v_mov_b32_e32 v145, v99
	v_mov_b32_e32 v147, v99
	v_mov_b32_e32 v159, v99
	v_mov_b32_e32 v161, v99
	v_mov_b32_e32 v163, v99
	v_mov_b32_e32 v165, v99
	v_mov_b32_e32 v167, v99
	v_mov_b32_e32 v169, v99
	v_mov_b32_e32 v171, v99
	v_mov_b32_e32 v173, v99
	v_mov_b32_e32 v175, v99
	s_waitcnt vmcnt(15)
	ds_write_b128 v26, v[8:11]
	v_add3_u32 v8, s2, v30, v31
	s_waitcnt vmcnt(14)
	ds_write_b128 v27, v[12:15]
	s_waitcnt vmcnt(13)
	ds_write_b128 v8, v[16:19]
	v_add3_u32 v8, s2, v32, v31
	s_waitcnt vmcnt(12)
	ds_write_b128 v8, v[20:23]
	s_nop 0
	s_nop 0
	s_add_i32 s2, 0, 0x14000
	s_waitcnt vmcnt(11)
	ds_write_b128 v26, v[100:103] offset:16384
	s_waitcnt vmcnt(10)
	ds_write_b128 v27, v[104:107] offset:16384
	v_add3_u32 v8, s2, v30, v31
	s_waitcnt vmcnt(9)
	ds_write_b128 v8, v[108:111]
	v_add3_u32 v8, s2, v32, v31
	s_waitcnt vmcnt(8)
	ds_write_b128 v8, v[112:115]
	s_nop 0
	s_nop 0
	s_add_i32 s2, 0, 0x18000
	s_waitcnt vmcnt(7)
	ds_write_b128 v26, v[116:119] offset:32768
	s_waitcnt vmcnt(6)
	ds_write_b128 v27, v[120:123] offset:32768
	v_add3_u32 v8, s2, v30, v31
	s_waitcnt vmcnt(5)
	ds_write_b128 v8, v[124:127]
	v_add3_u32 v8, s2, v32, v31
	s_waitcnt vmcnt(4)
	ds_write_b128 v8, v[128:131]
	s_nop 0
	s_nop 0
	s_add_i32 s2, 0, 0x1c000
	s_waitcnt vmcnt(3)
	ds_write_b128 v26, v[36:39] offset:49152
	s_waitcnt vmcnt(2)
	ds_write_b128 v27, v[40:43] offset:49152
	v_add3_u32 v8, s2, v30, v31
	v_bfe_u32 v12, v5, 5, 1
	v_lshlrev_b32_e32 v10, 4, v12
	s_waitcnt vmcnt(1)
	ds_write_b128 v8, v[44:47]
	v_add3_u32 v8, s2, v32, v31
	v_readfirstlane_b32 s2, v5
	s_ashr_i32 s3, s2, 1
	s_waitcnt vmcnt(0)
	ds_write_b128 v8, v[48:51]
	s_and_b32 s2, s3, 0xffffffe0
	v_mov_b32_e32 v8, s3
	s_movk_i32 s3, 0xffe0
	v_and_b32_e32 v14, 0xc0, v6
	v_bfi_b32 v8, s3, v8, v5
	v_lshlrev_b32_e32 v5, 8, v2
	v_and_b32_e32 v6, 0x70, v6
	v_or_b32_e32 v18, 0xe0, v10
	v_ashrrev_i32_e32 v9, 31, v8
	v_or_b32_e32 v17, 0xc0, v10
	v_bitop3_b32 v2, v18, v5, v6 bitop3:0xde
	v_lshlrev_b64 v[8:9], 10, v[8:9]
	v_or_b32_e32 v16, 0xa0, v10
	v_add_u32_e32 v178, 0, v2
	v_bitop3_b32 v2, v17, v5, v6 bitop3:0xde
	v_lshl_add_u64 v[8:9], s[0:1], 0, v[8:9]
	v_mov_b32_e32 v11, v99
	v_or_b32_e32 v15, 0x80, v10
	v_add_u32_e32 v179, 0, v2
	v_bitop3_b32 v2, v16, v5, v6 bitop3:0xde
	v_lshl_add_u64 v[132:133], v[8:9], 0, v[10:11]
	v_or_b32_e32 v11, 0x60, v10
	v_add_u32_e32 v180, 0, v2
	v_bitop3_b32 v2, v15, v5, v6 bitop3:0xde
	v_or_b32_e32 v9, 64, v10
	s_ashr_i32 s3, s2, 31
	v_add_u32_e32 v181, 0, v2
	v_bitop3_b32 v2, v11, v5, v6 bitop3:0xde
	v_or_b32_e32 v8, 32, v10
	s_lshl_b64 s[2:3], s[2:3], 12
	v_add_u32_e32 v182, 0, v2
	v_bitop3_b32 v2, v9, v5, v6 bitop3:0xde
	s_add_u32 s2, s4, s2
	v_add_u32_e32 v183, 0, v2
	v_bitop3_b32 v2, v8, v5, v6 bitop3:0xde
	v_and_b32_e32 v13, 24, v7
	v_and_b32_e32 v7, 0x100, v7
	s_addc_u32 s3, s5, s3
	v_add_u32_e32 v184, 0, v2
	v_bitop3_b32 v2, v10, v5, v6 bitop3:0xde
	v_lshl_add_u64 v[134:135], s[2:3], 0, v[98:99]
	v_lshlrev_b32_e32 v98, 14, v12
	v_add_u32_e32 v185, 0, v2
	v_add3_u32 v2, v7, 0, v14
	v_cmp_gt_u32_e64 s[0:1], 32, v4
	v_add_u32_e32 v177, s6, v10
	v_or_b32_e32 v136, 0x1000, v98
	v_or_b32_e32 v138, 0x2000, v98
	v_or_b32_e32 v140, 0x3000, v98
	v_or_b32_e32 v142, 0x8000, v98
	v_or_b32_e32 v144, 0x9000, v98
	v_or_b32_e32 v146, 0xa000, v98
	v_or_b32_e32 v158, 0xb000, v98
	v_or_b32_e32 v160, 0x10000, v98
	v_or_b32_e32 v162, 0x11000, v98
	v_or_b32_e32 v164, 0x12000, v98
	v_or_b32_e32 v166, 0x13000, v98
	v_or_b32_e32 v168, 0x18000, v98
	v_or_b32_e32 v170, 0x19000, v98
	v_or_b32_e32 v172, 0x1a000, v98
	v_or_b32_e32 v174, 0x1b000, v98
	v_add3_u32 v186, v2, v3, v13
	s_mov_b64 s[2:3], 0
	s_mov_b64 s[6:7], -1
	s_waitcnt lgkmcnt(0)
	s_barrier
	s_branch .LBB0_506
